# static priority raise for the second wave of each SIMD in the diff attention loop; MoBA store ladder without the never-taken exec branches
# speedup vs baseline: 1.0374x; 1.0010x over previous
.LBB0_654:
	s_or_b64 exec, exec, s[2:3]
	v_ashrrev_i32_e32 v83, 3, v80
	s_waitcnt lgkmcnt(0)
	v_rcp_f32_e32 v84, v76
	v_lshlrev_b32_e32 v82, 1, v81
	v_lshlrev_b32_e32 v81, 2, v83
	v_and_b32_e32 v81, -16, v81
	v_add_u32_e32 v83, s46, v81
	v_lshlrev_b32_e32 v76, 2, v80
	ds_read_b32 v81, v83 offset:256
	v_xor_b32_e32 v76, 4, v76
	v_mul_f32_e32 v16, v16, v84
	s_nop 1
	v_mov_b32_dpp v85, v16 quad_perm:[1,0,3,2] row_mask:0xf bank_mask:0xf
	v_and_b32_e32 v80, 1, v80
	s_waitcnt lgkmcnt(0)
	v_lshl_or_b32 v160, v81, 8, v82
	v_cmp_eq_u32_e32 vcc, 0, v80
	v_lshl_add_u64 v[80:81], s[12:13], 0, v[160:161]
	s_and_saveexec_b64 s[2:3], vcc
	s_waitcnt lgkmcnt(0)
	v_cvt_pk_bf16_f32 v16, v16, v85
	global_store_dword v[80:81], v16, off
.LBB0_656:
	s_or_b64 exec, exec, s[2:3]
	v_mul_f32_e32 v16, v32, v84
	s_nop 1
	v_mov_b32_dpp v32, v16 quad_perm:[1,0,3,2] row_mask:0xf bank_mask:0xf
	s_and_saveexec_b64 s[2:3], vcc
	s_waitcnt lgkmcnt(0)
	v_cvt_pk_bf16_f32 v16, v16, v32
	global_store_dword v[80:81], v16, off offset:64
.LBB0_658:
	s_or_b64 exec, exec, s[2:3]
	v_mul_f32_e32 v16, v48, v84
	s_waitcnt lgkmcnt(0)
	s_nop 1
	v_mov_b32_dpp v32, v16 quad_perm:[1,0,3,2] row_mask:0xf bank_mask:0xf
	s_and_saveexec_b64 s[2:3], vcc
	s_waitcnt lgkmcnt(0)
	v_cvt_pk_bf16_f32 v16, v16, v32
	global_store_dword v[80:81], v16, off offset:128
.LBB0_660:
	s_or_b64 exec, exec, s[2:3]
	v_mul_f32_e32 v0, v0, v84
	s_nop 1
	v_mov_b32_dpp v16, v0 quad_perm:[1,0,3,2] row_mask:0xf bank_mask:0xf
	s_and_saveexec_b64 s[2:3], vcc
	s_waitcnt lgkmcnt(0)
	v_cvt_pk_bf16_f32 v0, v0, v16
	global_store_dword v[80:81], v0, off offset:192
.LBB0_662:
	s_or_b64 exec, exec, s[2:3]
	v_rcp_f32_e32 v0, v77
	s_waitcnt lgkmcnt(0)
	ds_read_b32 v16, v83 offset:260
	v_mul_f32_e32 v32, v17, v0
	s_nop 1
	v_mov_b32_dpp v48, v32 quad_perm:[1,0,3,2] row_mask:0xf bank_mask:0xf
	s_waitcnt lgkmcnt(0)
	v_lshl_or_b32 v160, v16, 8, v82
	v_lshl_add_u64 v[16:17], s[12:13], 0, v[160:161]
	s_and_saveexec_b64 s[2:3], vcc
	s_waitcnt lgkmcnt(0)
	v_cvt_pk_bf16_f32 v32, v32, v48
	global_store_dword v[16:17], v32, off
.LBB0_664:
	s_or_b64 exec, exec, s[2:3]
	v_mul_f32_e32 v32, v33, v0
	s_nop 1
	v_mov_b32_dpp v33, v32 quad_perm:[1,0,3,2] row_mask:0xf bank_mask:0xf
	s_and_saveexec_b64 s[2:3], vcc
	s_waitcnt lgkmcnt(0)
	v_cvt_pk_bf16_f32 v32, v32, v33
	global_store_dword v[16:17], v32, off offset:64
.LBB0_666:
	s_or_b64 exec, exec, s[2:3]
	v_mul_f32_e32 v32, v49, v0
	s_waitcnt lgkmcnt(0)
	s_nop 1
	v_mov_b32_dpp v33, v32 quad_perm:[1,0,3,2] row_mask:0xf bank_mask:0xf
	s_and_saveexec_b64 s[2:3], vcc
	s_waitcnt lgkmcnt(0)
	v_cvt_pk_bf16_f32 v32, v32, v33
	global_store_dword v[16:17], v32, off offset:128
.LBB0_668:
	s_or_b64 exec, exec, s[2:3]
	v_mul_f32_e32 v0, v1, v0
	s_nop 1
	v_mov_b32_dpp v1, v0 quad_perm:[1,0,3,2] row_mask:0xf bank_mask:0xf
	s_and_saveexec_b64 s[2:3], vcc
	s_waitcnt lgkmcnt(0)
	v_cvt_pk_bf16_f32 v0, v0, v1
	global_store_dword v[16:17], v0, off offset:192
.LBB0_670:
	s_or_b64 exec, exec, s[2:3]
	v_rcp_f32_e32 v16, v78
	ds_read_b32 v0, v83 offset:264
	v_mul_f32_e32 v17, v18, v16
	s_nop 1
	v_mov_b32_dpp v18, v17 quad_perm:[1,0,3,2] row_mask:0xf bank_mask:0xf
	s_waitcnt lgkmcnt(0)
	v_lshl_or_b32 v160, v0, 8, v82
	v_lshl_add_u64 v[0:1], s[12:13], 0, v[160:161]
	s_and_saveexec_b64 s[2:3], vcc
	s_waitcnt lgkmcnt(0)
	v_cvt_pk_bf16_f32 v17, v17, v18
	global_store_dword v[0:1], v17, off
.LBB0_672:
	s_or_b64 exec, exec, s[2:3]
	v_mul_f32_e32 v17, v34, v16
	s_waitcnt lgkmcnt(0)
	s_nop 1
	v_mov_b32_dpp v18, v17 quad_perm:[1,0,3,2] row_mask:0xf bank_mask:0xf
	s_and_saveexec_b64 s[2:3], vcc
	s_waitcnt lgkmcnt(0)
	v_cvt_pk_bf16_f32 v17, v17, v18
	global_store_dword v[0:1], v17, off offset:64
.LBB0_674:
	s_or_b64 exec, exec, s[2:3]
	v_mul_f32_e32 v17, v50, v16
	s_waitcnt lgkmcnt(0)
	s_nop 1
	v_mov_b32_dpp v18, v17 quad_perm:[1,0,3,2] row_mask:0xf bank_mask:0xf
	s_and_saveexec_b64 s[2:3], vcc
	s_waitcnt lgkmcnt(0)
	v_cvt_pk_bf16_f32 v17, v17, v18
	global_store_dword v[0:1], v17, off offset:128
.LBB0_676:
	s_or_b64 exec, exec, s[2:3]
	v_mul_f32_e32 v2, v2, v16
	s_nop 1
	v_mov_b32_dpp v16, v2 quad_perm:[1,0,3,2] row_mask:0xf bank_mask:0xf
	s_and_saveexec_b64 s[2:3], vcc
	s_waitcnt lgkmcnt(0)
	v_cvt_pk_bf16_f32 v2, v2, v16
	global_store_dword v[0:1], v2, off offset:192
.LBB0_678:
	s_or_b64 exec, exec, s[2:3]
	v_rcp_f32_e32 v2, v79
	ds_read_b32 v0, v83 offset:268
	s_waitcnt lgkmcnt(0)
	v_mul_f32_e32 v16, v19, v2
	s_nop 1
	v_mov_b32_dpp v17, v16 quad_perm:[1,0,3,2] row_mask:0xf bank_mask:0xf
	s_waitcnt lgkmcnt(0)
	v_lshl_or_b32 v160, v0, 8, v82
	v_lshl_add_u64 v[0:1], s[12:13], 0, v[160:161]
	s_and_saveexec_b64 s[2:3], vcc
	s_waitcnt lgkmcnt(0)
	v_cvt_pk_bf16_f32 v16, v16, v17
	global_store_dword v[0:1], v16, off
.LBB0_680:
	s_or_b64 exec, exec, s[2:3]
	v_mul_f32_e32 v16, v35, v2
	s_waitcnt lgkmcnt(0)
	s_nop 1
	v_mov_b32_dpp v17, v16 quad_perm:[1,0,3,2] row_mask:0xf bank_mask:0xf
	s_and_saveexec_b64 s[2:3], vcc
	s_waitcnt lgkmcnt(0)
	v_cvt_pk_bf16_f32 v16, v16, v17
	global_store_dword v[0:1], v16, off offset:64
.LBB0_682:
	s_or_b64 exec, exec, s[2:3]
	v_mul_f32_e32 v16, v51, v2
	s_waitcnt lgkmcnt(0)
	s_nop 1
	v_mov_b32_dpp v17, v16 quad_perm:[1,0,3,2] row_mask:0xf bank_mask:0xf
	s_and_saveexec_b64 s[2:3], vcc
	s_waitcnt lgkmcnt(0)
	v_cvt_pk_bf16_f32 v16, v16, v17
	global_store_dword v[0:1], v16, off offset:128
.LBB0_684:
	s_or_b64 exec, exec, s[2:3]
	v_mul_f32_e32 v2, v3, v2
	s_nop 1
	v_mov_b32_dpp v3, v2 quad_perm:[1,0,3,2] row_mask:0xf bank_mask:0xf
	s_and_saveexec_b64 s[2:3], vcc
	s_waitcnt lgkmcnt(0)
	v_cvt_pk_bf16_f32 v2, v2, v3
	global_store_dword v[0:1], v2, off offset:192
.LBB0_686:
	s_or_b64 exec, exec, s[2:3]
	v_rcp_f32_e32 v2, v72
	ds_read_b32 v0, v83 offset:288
	s_waitcnt lgkmcnt(0)
	v_mul_f32_e32 v3, v20, v2
	s_nop 1
	v_mov_b32_dpp v16, v3 quad_perm:[1,0,3,2] row_mask:0xf bank_mask:0xf
	s_waitcnt lgkmcnt(0)
	v_lshl_or_b32 v160, v0, 8, v82
	v_lshl_add_u64 v[0:1], s[12:13], 0, v[160:161]
	s_and_saveexec_b64 s[2:3], vcc
	s_waitcnt lgkmcnt(0)
	v_cvt_pk_bf16_f32 v3, v3, v16
	global_store_dword v[0:1], v3, off
.LBB0_688:
	s_or_b64 exec, exec, s[2:3]
	v_mul_f32_e32 v3, v36, v2
	s_waitcnt lgkmcnt(0)
	s_nop 1
	v_mov_b32_dpp v16, v3 quad_perm:[1,0,3,2] row_mask:0xf bank_mask:0xf
	s_and_saveexec_b64 s[2:3], vcc
	s_waitcnt lgkmcnt(0)
	v_cvt_pk_bf16_f32 v3, v3, v16
	global_store_dword v[0:1], v3, off offset:64
.LBB0_690:
	s_or_b64 exec, exec, s[2:3]
	v_mul_f32_e32 v3, v52, v2
	s_waitcnt lgkmcnt(0)
	s_nop 1
	v_mov_b32_dpp v16, v3 quad_perm:[1,0,3,2] row_mask:0xf bank_mask:0xf
	s_and_saveexec_b64 s[2:3], vcc
	s_waitcnt lgkmcnt(0)
	v_cvt_pk_bf16_f32 v3, v3, v16
	global_store_dword v[0:1], v3, off offset:128
.LBB0_692:
	s_or_b64 exec, exec, s[2:3]
	v_mul_f32_e32 v2, v4, v2
	s_nop 1
	v_mov_b32_dpp v3, v2 quad_perm:[1,0,3,2] row_mask:0xf bank_mask:0xf
	s_and_saveexec_b64 s[2:3], vcc
	s_waitcnt lgkmcnt(0)
	v_cvt_pk_bf16_f32 v2, v2, v3
	global_store_dword v[0:1], v2, off offset:192
.LBB0_694:
	s_or_b64 exec, exec, s[2:3]
	v_rcp_f32_e32 v2, v73
	ds_read_b32 v0, v83 offset:292
	s_waitcnt lgkmcnt(0)
	v_mul_f32_e32 v3, v21, v2
	s_nop 1
	v_mov_b32_dpp v4, v3 quad_perm:[1,0,3,2] row_mask:0xf bank_mask:0xf
	s_waitcnt lgkmcnt(0)
	v_lshl_or_b32 v160, v0, 8, v82
	v_lshl_add_u64 v[0:1], s[12:13], 0, v[160:161]
	s_and_saveexec_b64 s[2:3], vcc
	s_waitcnt lgkmcnt(0)
	v_cvt_pk_bf16_f32 v3, v3, v4
	global_store_dword v[0:1], v3, off
.LBB0_696:
	s_or_b64 exec, exec, s[2:3]
	v_mul_f32_e32 v3, v37, v2
	s_waitcnt lgkmcnt(0)
	s_nop 1
	v_mov_b32_dpp v4, v3 quad_perm:[1,0,3,2] row_mask:0xf bank_mask:0xf
	s_and_saveexec_b64 s[2:3], vcc
	s_waitcnt lgkmcnt(0)
	v_cvt_pk_bf16_f32 v3, v3, v4
	global_store_dword v[0:1], v3, off offset:64
.LBB0_698:
	s_or_b64 exec, exec, s[2:3]
	v_mul_f32_e32 v3, v53, v2
	s_waitcnt lgkmcnt(0)
	s_nop 1
	v_mov_b32_dpp v4, v3 quad_perm:[1,0,3,2] row_mask:0xf bank_mask:0xf
	s_and_saveexec_b64 s[2:3], vcc
	s_waitcnt lgkmcnt(0)
	v_cvt_pk_bf16_f32 v3, v3, v4
	global_store_dword v[0:1], v3, off offset:128
.LBB0_700:
	s_or_b64 exec, exec, s[2:3]
	v_mul_f32_e32 v2, v5, v2
	s_nop 1
	v_mov_b32_dpp v3, v2 quad_perm:[1,0,3,2] row_mask:0xf bank_mask:0xf
	s_and_saveexec_b64 s[2:3], vcc
	s_waitcnt lgkmcnt(0)
	v_cvt_pk_bf16_f32 v2, v2, v3
	global_store_dword v[0:1], v2, off offset:192
.LBB0_702:
	s_or_b64 exec, exec, s[2:3]
	v_rcp_f32_e32 v2, v74
	ds_read_b32 v0, v83 offset:296
	s_waitcnt lgkmcnt(0)
	v_mul_f32_e32 v3, v22, v2
	s_nop 1
	v_mov_b32_dpp v4, v3 quad_perm:[1,0,3,2] row_mask:0xf bank_mask:0xf
	s_waitcnt lgkmcnt(0)
	v_lshl_or_b32 v160, v0, 8, v82
	v_lshl_add_u64 v[0:1], s[12:13], 0, v[160:161]
	s_and_saveexec_b64 s[2:3], vcc
	s_waitcnt lgkmcnt(0)
	v_cvt_pk_bf16_f32 v3, v3, v4
	global_store_dword v[0:1], v3, off
.LBB0_704:
	s_or_b64 exec, exec, s[2:3]
	v_mul_f32_e32 v3, v38, v2
	s_waitcnt lgkmcnt(0)
	s_nop 1
	v_mov_b32_dpp v4, v3 quad_perm:[1,0,3,2] row_mask:0xf bank_mask:0xf
	s_and_saveexec_b64 s[2:3], vcc
	s_waitcnt lgkmcnt(0)
	v_cvt_pk_bf16_f32 v3, v3, v4
	global_store_dword v[0:1], v3, off offset:64
.LBB0_706:
	s_or_b64 exec, exec, s[2:3]
	v_mul_f32_e32 v3, v54, v2
	s_waitcnt lgkmcnt(0)
	s_nop 1
	v_mov_b32_dpp v4, v3 quad_perm:[1,0,3,2] row_mask:0xf bank_mask:0xf
	s_and_saveexec_b64 s[2:3], vcc
	s_waitcnt lgkmcnt(0)
	v_cvt_pk_bf16_f32 v3, v3, v4
	global_store_dword v[0:1], v3, off offset:128
.LBB0_708:
	s_or_b64 exec, exec, s[2:3]
	v_mul_f32_e32 v2, v6, v2
	s_nop 1
	v_mov_b32_dpp v3, v2 quad_perm:[1,0,3,2] row_mask:0xf bank_mask:0xf
	s_and_saveexec_b64 s[2:3], vcc
	s_waitcnt lgkmcnt(0)
	v_cvt_pk_bf16_f32 v2, v2, v3
	global_store_dword v[0:1], v2, off offset:192
.LBB0_710:
	s_or_b64 exec, exec, s[2:3]
	v_rcp_f32_e32 v2, v75
	ds_read_b32 v0, v83 offset:300
	s_waitcnt lgkmcnt(0)
	v_mul_f32_e32 v3, v23, v2
	s_nop 1
	v_mov_b32_dpp v4, v3 quad_perm:[1,0,3,2] row_mask:0xf bank_mask:0xf
	s_waitcnt lgkmcnt(0)
	v_lshl_or_b32 v160, v0, 8, v82
	v_lshl_add_u64 v[0:1], s[12:13], 0, v[160:161]
	s_and_saveexec_b64 s[2:3], vcc
	s_waitcnt lgkmcnt(0)
	v_cvt_pk_bf16_f32 v3, v3, v4
	global_store_dword v[0:1], v3, off
.LBB0_712:
	s_or_b64 exec, exec, s[2:3]
	v_mul_f32_e32 v3, v39, v2
	s_waitcnt lgkmcnt(0)
	s_nop 1
	v_mov_b32_dpp v4, v3 quad_perm:[1,0,3,2] row_mask:0xf bank_mask:0xf
	s_and_saveexec_b64 s[2:3], vcc
	s_waitcnt lgkmcnt(0)
	v_cvt_pk_bf16_f32 v3, v3, v4
	global_store_dword v[0:1], v3, off offset:64
.LBB0_714:
	s_or_b64 exec, exec, s[2:3]
	v_mul_f32_e32 v3, v55, v2
	s_waitcnt lgkmcnt(0)
	s_nop 1
	v_mov_b32_dpp v4, v3 quad_perm:[1,0,3,2] row_mask:0xf bank_mask:0xf
	s_and_saveexec_b64 s[2:3], vcc
	s_waitcnt lgkmcnt(0)
	v_cvt_pk_bf16_f32 v3, v3, v4
	global_store_dword v[0:1], v3, off offset:128
.LBB0_716:
	s_or_b64 exec, exec, s[2:3]
	v_mul_f32_e32 v2, v7, v2
	s_nop 1
	v_mov_b32_dpp v3, v2 quad_perm:[1,0,3,2] row_mask:0xf bank_mask:0xf
	s_and_saveexec_b64 s[2:3], vcc
	s_waitcnt lgkmcnt(0)
	v_cvt_pk_bf16_f32 v2, v2, v3
	global_store_dword v[0:1], v2, off offset:192
.LBB0_718:
	s_or_b64 exec, exec, s[2:3]
	v_rcp_f32_e32 v2, v68
	ds_read_b32 v0, v83 offset:320
	s_waitcnt lgkmcnt(0)
	v_mul_f32_e32 v3, v24, v2
	s_nop 1
	v_mov_b32_dpp v4, v3 quad_perm:[1,0,3,2] row_mask:0xf bank_mask:0xf
	s_waitcnt lgkmcnt(0)
	v_lshl_or_b32 v160, v0, 8, v82
	v_lshl_add_u64 v[0:1], s[12:13], 0, v[160:161]
	s_and_saveexec_b64 s[2:3], vcc
	s_waitcnt lgkmcnt(0)
	v_cvt_pk_bf16_f32 v3, v3, v4
	global_store_dword v[0:1], v3, off
.LBB0_720:
	s_or_b64 exec, exec, s[2:3]
	v_mul_f32_e32 v3, v40, v2
	s_waitcnt lgkmcnt(0)
	s_nop 1
	v_mov_b32_dpp v4, v3 quad_perm:[1,0,3,2] row_mask:0xf bank_mask:0xf
	s_and_saveexec_b64 s[2:3], vcc
	s_waitcnt lgkmcnt(0)
	v_cvt_pk_bf16_f32 v3, v3, v4
	global_store_dword v[0:1], v3, off offset:64
.LBB0_722:
	s_or_b64 exec, exec, s[2:3]
	v_mul_f32_e32 v3, v56, v2
	s_waitcnt lgkmcnt(0)
	s_nop 1
	v_mov_b32_dpp v4, v3 quad_perm:[1,0,3,2] row_mask:0xf bank_mask:0xf
	s_and_saveexec_b64 s[2:3], vcc
	s_waitcnt lgkmcnt(0)
	v_cvt_pk_bf16_f32 v3, v3, v4
	global_store_dword v[0:1], v3, off offset:128
.LBB0_724:
	s_or_b64 exec, exec, s[2:3]
	v_mul_f32_e32 v2, v8, v2
	s_nop 1
	v_mov_b32_dpp v3, v2 quad_perm:[1,0,3,2] row_mask:0xf bank_mask:0xf
	s_and_saveexec_b64 s[2:3], vcc
	s_waitcnt lgkmcnt(0)
	v_cvt_pk_bf16_f32 v2, v2, v3
	global_store_dword v[0:1], v2, off offset:192
.LBB0_726:
	s_or_b64 exec, exec, s[2:3]
	v_rcp_f32_e32 v2, v69
	ds_read_b32 v0, v83 offset:324
	s_waitcnt lgkmcnt(0)
	v_mul_f32_e32 v3, v25, v2
	s_nop 1
	v_mov_b32_dpp v4, v3 quad_perm:[1,0,3,2] row_mask:0xf bank_mask:0xf
	s_waitcnt lgkmcnt(0)
	v_lshl_or_b32 v160, v0, 8, v82
	v_lshl_add_u64 v[0:1], s[12:13], 0, v[160:161]
	s_and_saveexec_b64 s[2:3], vcc
	s_waitcnt lgkmcnt(0)
	v_cvt_pk_bf16_f32 v3, v3, v4
	global_store_dword v[0:1], v3, off
.LBB0_728:
	s_or_b64 exec, exec, s[2:3]
	v_mul_f32_e32 v3, v41, v2
	s_waitcnt lgkmcnt(0)
	s_nop 1
	v_mov_b32_dpp v4, v3 quad_perm:[1,0,3,2] row_mask:0xf bank_mask:0xf
	s_and_saveexec_b64 s[2:3], vcc
	s_waitcnt lgkmcnt(0)
	v_cvt_pk_bf16_f32 v3, v3, v4
	global_store_dword v[0:1], v3, off offset:64
.LBB0_730:
	s_or_b64 exec, exec, s[2:3]
	v_mul_f32_e32 v3, v57, v2
	s_waitcnt lgkmcnt(0)
	s_nop 1
	v_mov_b32_dpp v4, v3 quad_perm:[1,0,3,2] row_mask:0xf bank_mask:0xf
	s_and_saveexec_b64 s[2:3], vcc
	s_waitcnt lgkmcnt(0)
	v_cvt_pk_bf16_f32 v3, v3, v4
	global_store_dword v[0:1], v3, off offset:128
.LBB0_732:
	s_or_b64 exec, exec, s[2:3]
	v_mul_f32_e32 v2, v9, v2
	s_nop 1
	v_mov_b32_dpp v3, v2 quad_perm:[1,0,3,2] row_mask:0xf bank_mask:0xf
	s_and_saveexec_b64 s[2:3], vcc
	s_waitcnt lgkmcnt(0)
	v_cvt_pk_bf16_f32 v2, v2, v3
	global_store_dword v[0:1], v2, off offset:192
.LBB0_734:
	s_or_b64 exec, exec, s[2:3]
	v_rcp_f32_e32 v2, v70
	ds_read_b32 v0, v83 offset:328
	s_waitcnt lgkmcnt(0)
	v_mul_f32_e32 v3, v26, v2
	s_nop 1
	v_mov_b32_dpp v4, v3 quad_perm:[1,0,3,2] row_mask:0xf bank_mask:0xf
	s_waitcnt lgkmcnt(0)
	v_lshl_or_b32 v160, v0, 8, v82
	v_lshl_add_u64 v[0:1], s[12:13], 0, v[160:161]
	s_and_saveexec_b64 s[2:3], vcc
	s_waitcnt lgkmcnt(0)
	v_cvt_pk_bf16_f32 v3, v3, v4
	global_store_dword v[0:1], v3, off
.LBB0_736:
	s_or_b64 exec, exec, s[2:3]
	v_mul_f32_e32 v3, v42, v2
	s_waitcnt lgkmcnt(0)
	s_nop 1
	v_mov_b32_dpp v4, v3 quad_perm:[1,0,3,2] row_mask:0xf bank_mask:0xf
	s_and_saveexec_b64 s[2:3], vcc
	s_waitcnt lgkmcnt(0)
	v_cvt_pk_bf16_f32 v3, v3, v4
	global_store_dword v[0:1], v3, off offset:64
.LBB0_738:
	s_or_b64 exec, exec, s[2:3]
	v_mul_f32_e32 v3, v58, v2
	s_waitcnt lgkmcnt(0)
	s_nop 1
	v_mov_b32_dpp v4, v3 quad_perm:[1,0,3,2] row_mask:0xf bank_mask:0xf
	s_and_saveexec_b64 s[2:3], vcc
	s_waitcnt lgkmcnt(0)
	v_cvt_pk_bf16_f32 v3, v3, v4
	global_store_dword v[0:1], v3, off offset:128
.LBB0_740:
	s_or_b64 exec, exec, s[2:3]
	v_mul_f32_e32 v2, v10, v2
	s_nop 1
	v_mov_b32_dpp v3, v2 quad_perm:[1,0,3,2] row_mask:0xf bank_mask:0xf
	s_and_saveexec_b64 s[2:3], vcc
	s_waitcnt lgkmcnt(0)
	v_cvt_pk_bf16_f32 v2, v2, v3
	global_store_dword v[0:1], v2, off offset:192
.LBB0_742:
	s_or_b64 exec, exec, s[2:3]
	v_rcp_f32_e32 v2, v71
	ds_read_b32 v0, v83 offset:332
	s_waitcnt lgkmcnt(0)
	v_mul_f32_e32 v3, v27, v2
	s_nop 1
	v_mov_b32_dpp v4, v3 quad_perm:[1,0,3,2] row_mask:0xf bank_mask:0xf
	s_waitcnt lgkmcnt(0)
	v_lshl_or_b32 v160, v0, 8, v82
	v_lshl_add_u64 v[0:1], s[12:13], 0, v[160:161]
	s_and_saveexec_b64 s[2:3], vcc
	s_waitcnt lgkmcnt(0)
	v_cvt_pk_bf16_f32 v3, v3, v4
	global_store_dword v[0:1], v3, off
.LBB0_744:
	s_or_b64 exec, exec, s[2:3]
	v_mul_f32_e32 v3, v43, v2
	s_waitcnt lgkmcnt(0)
	s_nop 1
	v_mov_b32_dpp v4, v3 quad_perm:[1,0,3,2] row_mask:0xf bank_mask:0xf
	s_and_saveexec_b64 s[2:3], vcc
	s_waitcnt lgkmcnt(0)
	v_cvt_pk_bf16_f32 v3, v3, v4
	global_store_dword v[0:1], v3, off offset:64
.LBB0_746:
	s_or_b64 exec, exec, s[2:3]
	v_mul_f32_e32 v3, v59, v2
	s_waitcnt lgkmcnt(0)
	s_nop 1
	v_mov_b32_dpp v4, v3 quad_perm:[1,0,3,2] row_mask:0xf bank_mask:0xf
	s_and_saveexec_b64 s[2:3], vcc
	s_waitcnt lgkmcnt(0)
	v_cvt_pk_bf16_f32 v3, v3, v4
	global_store_dword v[0:1], v3, off offset:128
.LBB0_748:
	s_or_b64 exec, exec, s[2:3]
	v_mul_f32_e32 v2, v11, v2
	s_nop 1
	v_mov_b32_dpp v3, v2 quad_perm:[1,0,3,2] row_mask:0xf bank_mask:0xf
	s_and_saveexec_b64 s[2:3], vcc
	s_waitcnt lgkmcnt(0)
	v_cvt_pk_bf16_f32 v2, v2, v3
	global_store_dword v[0:1], v2, off offset:192
.LBB0_750:
	s_or_b64 exec, exec, s[2:3]
	v_rcp_f32_e32 v2, v64
	ds_read_b32 v0, v83 offset:352
	s_waitcnt lgkmcnt(0)
	v_mul_f32_e32 v3, v28, v2
	s_nop 1
	v_mov_b32_dpp v4, v3 quad_perm:[1,0,3,2] row_mask:0xf bank_mask:0xf
	s_waitcnt lgkmcnt(0)
	v_lshl_or_b32 v160, v0, 8, v82
	v_lshl_add_u64 v[0:1], s[12:13], 0, v[160:161]
	s_and_saveexec_b64 s[2:3], vcc
	s_waitcnt lgkmcnt(0)
	v_cvt_pk_bf16_f32 v3, v3, v4
	global_store_dword v[0:1], v3, off
.LBB0_752:
	s_or_b64 exec, exec, s[2:3]
	v_mul_f32_e32 v3, v44, v2
	s_waitcnt lgkmcnt(0)
	s_nop 1
	v_mov_b32_dpp v4, v3 quad_perm:[1,0,3,2] row_mask:0xf bank_mask:0xf
	s_and_saveexec_b64 s[2:3], vcc
	s_waitcnt lgkmcnt(0)
	v_cvt_pk_bf16_f32 v3, v3, v4
	global_store_dword v[0:1], v3, off offset:64
.LBB0_754:
	s_or_b64 exec, exec, s[2:3]
	v_mul_f32_e32 v3, v60, v2
	s_waitcnt lgkmcnt(0)
	s_nop 1
	v_mov_b32_dpp v4, v3 quad_perm:[1,0,3,2] row_mask:0xf bank_mask:0xf
	s_and_saveexec_b64 s[2:3], vcc
	s_waitcnt lgkmcnt(0)
	v_cvt_pk_bf16_f32 v3, v3, v4
	global_store_dword v[0:1], v3, off offset:128
.LBB0_756:
	s_or_b64 exec, exec, s[2:3]
	v_mul_f32_e32 v2, v12, v2
	s_nop 1
	v_mov_b32_dpp v3, v2 quad_perm:[1,0,3,2] row_mask:0xf bank_mask:0xf
	s_and_saveexec_b64 s[2:3], vcc
	s_waitcnt lgkmcnt(0)
	v_cvt_pk_bf16_f32 v2, v2, v3
	global_store_dword v[0:1], v2, off offset:192
.LBB0_758:
	s_or_b64 exec, exec, s[2:3]
	v_rcp_f32_e32 v2, v65
	ds_read_b32 v0, v83 offset:356
	s_waitcnt lgkmcnt(0)
	v_mul_f32_e32 v3, v29, v2
	s_nop 1
	v_mov_b32_dpp v4, v3 quad_perm:[1,0,3,2] row_mask:0xf bank_mask:0xf
	s_waitcnt lgkmcnt(0)
	v_lshl_or_b32 v160, v0, 8, v82
	v_lshl_add_u64 v[0:1], s[12:13], 0, v[160:161]
	s_and_saveexec_b64 s[2:3], vcc
	s_waitcnt lgkmcnt(0)
	v_cvt_pk_bf16_f32 v3, v3, v4
	global_store_dword v[0:1], v3, off
.LBB0_760:
	s_or_b64 exec, exec, s[2:3]
	v_mul_f32_e32 v3, v45, v2
	s_waitcnt lgkmcnt(0)
	s_nop 1
	v_mov_b32_dpp v4, v3 quad_perm:[1,0,3,2] row_mask:0xf bank_mask:0xf
	s_and_saveexec_b64 s[2:3], vcc
	s_waitcnt lgkmcnt(0)
	v_cvt_pk_bf16_f32 v3, v3, v4
	global_store_dword v[0:1], v3, off offset:64
.LBB0_762:
	s_or_b64 exec, exec, s[2:3]
	v_mul_f32_e32 v3, v61, v2
	s_waitcnt lgkmcnt(0)
	s_nop 1
	v_mov_b32_dpp v4, v3 quad_perm:[1,0,3,2] row_mask:0xf bank_mask:0xf
	s_and_saveexec_b64 s[2:3], vcc
	s_waitcnt lgkmcnt(0)
	v_cvt_pk_bf16_f32 v3, v3, v4
	global_store_dword v[0:1], v3, off offset:128
.LBB0_764:
	s_or_b64 exec, exec, s[2:3]
	v_mul_f32_e32 v2, v13, v2
	s_nop 1
	v_mov_b32_dpp v3, v2 quad_perm:[1,0,3,2] row_mask:0xf bank_mask:0xf
	s_and_saveexec_b64 s[2:3], vcc
	s_waitcnt lgkmcnt(0)
	v_cvt_pk_bf16_f32 v2, v2, v3
	global_store_dword v[0:1], v2, off offset:192
.LBB0_766:
	s_or_b64 exec, exec, s[2:3]
	v_rcp_f32_e32 v2, v66
	ds_read_b32 v0, v83 offset:360
	s_waitcnt lgkmcnt(0)
	v_mul_f32_e32 v3, v30, v2
	s_nop 1
	v_mov_b32_dpp v4, v3 quad_perm:[1,0,3,2] row_mask:0xf bank_mask:0xf
	s_waitcnt lgkmcnt(0)
	v_lshl_or_b32 v160, v0, 8, v82
	v_lshl_add_u64 v[0:1], s[12:13], 0, v[160:161]
	s_and_saveexec_b64 s[2:3], vcc
	s_waitcnt lgkmcnt(0)
	v_cvt_pk_bf16_f32 v3, v3, v4
	global_store_dword v[0:1], v3, off
.LBB0_768:
	s_or_b64 exec, exec, s[2:3]
	v_mul_f32_e32 v3, v46, v2
	s_waitcnt lgkmcnt(0)
	s_nop 1
	v_mov_b32_dpp v4, v3 quad_perm:[1,0,3,2] row_mask:0xf bank_mask:0xf
	s_and_saveexec_b64 s[2:3], vcc
	s_waitcnt lgkmcnt(0)
	v_cvt_pk_bf16_f32 v3, v3, v4
	global_store_dword v[0:1], v3, off offset:64
.LBB0_770:
	s_or_b64 exec, exec, s[2:3]
	v_mul_f32_e32 v3, v62, v2
	s_waitcnt lgkmcnt(0)
	s_nop 1
	v_mov_b32_dpp v4, v3 quad_perm:[1,0,3,2] row_mask:0xf bank_mask:0xf
	s_and_saveexec_b64 s[2:3], vcc
	s_waitcnt lgkmcnt(0)
	v_cvt_pk_bf16_f32 v3, v3, v4
	global_store_dword v[0:1], v3, off offset:128
.LBB0_772:
	s_or_b64 exec, exec, s[2:3]
	v_mul_f32_e32 v2, v14, v2
	s_nop 1
	v_mov_b32_dpp v3, v2 quad_perm:[1,0,3,2] row_mask:0xf bank_mask:0xf
	s_and_saveexec_b64 s[2:3], vcc
	s_waitcnt lgkmcnt(0)
	v_cvt_pk_bf16_f32 v2, v2, v3
	global_store_dword v[0:1], v2, off offset:192
.LBB0_774:
	s_or_b64 exec, exec, s[2:3]
	v_rcp_f32_e32 v2, v67
	ds_read_b32 v0, v83 offset:364
	s_waitcnt lgkmcnt(0)
	v_mul_f32_e32 v3, v31, v2
	s_nop 1
	v_mov_b32_dpp v4, v3 quad_perm:[1,0,3,2] row_mask:0xf bank_mask:0xf
	s_waitcnt lgkmcnt(0)
	v_lshl_or_b32 v160, v0, 8, v82
	v_lshl_add_u64 v[0:1], s[12:13], 0, v[160:161]
	s_and_saveexec_b64 s[2:3], vcc
	s_waitcnt lgkmcnt(0)
	v_cvt_pk_bf16_f32 v3, v3, v4
	global_store_dword v[0:1], v3, off
.LBB0_776:
	s_or_b64 exec, exec, s[2:3]
	v_mul_f32_e32 v3, v47, v2
	s_waitcnt lgkmcnt(0)
	s_nop 1
	v_mov_b32_dpp v4, v3 quad_perm:[1,0,3,2] row_mask:0xf bank_mask:0xf
	s_and_saveexec_b64 s[2:3], vcc
	s_waitcnt lgkmcnt(0)
	v_cvt_pk_bf16_f32 v3, v3, v4
	global_store_dword v[0:1], v3, off offset:64
.LBB0_778:
	s_or_b64 exec, exec, s[2:3]
	v_mul_f32_e32 v3, v63, v2
	s_waitcnt lgkmcnt(0)
	s_nop 1
	v_mov_b32_dpp v4, v3 quad_perm:[1,0,3,2] row_mask:0xf bank_mask:0xf
	s_and_saveexec_b64 s[2:3], vcc
	s_waitcnt lgkmcnt(0)
	v_cvt_pk_bf16_f32 v3, v3, v4
	global_store_dword v[0:1], v3, off offset:128

.LBB0_785:
	s_lshr_b32 s52, s51, 1
	s_lshl_b32 s2, s52, 7
	v_readlane_b32 s3, v251, 38
	s_add_i32 s4, s3, s2
	s_lshl_b64 s[34:35], s[4:5], 1
	s_bitcmp0_b32 s51, 0
	v_readlane_b32 s2, v251, 34
	v_readlane_b32 s3, v251, 36
	s_cselect_b32 s3, s3, s2
	v_readlane_b32 s60, v251, 32
	v_readlane_b32 s61, v251, 33
	s_or_b32 s2, s60, s3
	s_mul_i32 s30, s61, 0x3000
	s_mul_hi_u32 s4, s2, 0x3000
	v_writelane_b32 v251, s30, 44
	s_add_i32 s4, s4, s30
	s_mul_i32 s30, s2, 0x3000
	s_add_u32 s30, s48, s30
	s_addc_u32 s4, s49, s4
	s_add_u32 s38, s30, s34
	s_addc_u32 s39, s4, s35
	s_add_u32 s36, s40, s34
	v_readfirstlane_b32 s4, v208
	s_addc_u32 s37, s41, s35
	s_ashr_i32 s56, s4, 6
	s_and_b32 s4, s4, 0x3fffffc0
	s_lshl_b32 s4, s4, 2
	s_lshl_b32 s31, s56, 3
	s_lshl_b32 s30, s56, 5
	s_add_i32 s4, s4, 0
	v_or_b32_e32 v0, s31, v212
	v_bitop3_b32 v7, s31, v229, v214 bitop3:0xc8
	s_lshl_b32 s31, s56, 2
	s_add_i32 s57, s4, 0x18000
	s_add_i32 s4, s30, s3
	s_and_b32 s58, s31, 4
	s_lshl_b32 s53, s56, 11
	s_lshl_b32 s54, s56, 12
	s_ashr_i32 s31, s30, 31
	s_mul_i32 s55, s56, 0x60000
	s_mul_hi_i32 s59, s30, 0x3000
	s_add_u32 s38, s38, s55
	v_or3_b32 v2, v215, v7, s58
	s_addc_u32 s39, s39, s59
	s_lshr_b32 s3, s3, 6
	v_mul_lo_u32 v2, v2, s45
	s_or_b32 s55, s3, 3
	v_or_b32_e32 v8, v2, v216
	v_lshl_add_u64 v[2:3], s[38:39], 0, v[194:195]
	s_mov_b64 s[38:39], 0x30000
	s_cmp_lg_u32 0, -1
	v_lshl_add_u64 v[4:5], v[2:3], 0, s[38:39]
	s_movk_i32 s38, 0x1000
	s_cselect_b32 s3, 0, 0
	v_mul_lo_u32 v0, v0, s44
	s_add_i32 s38, s3, s53
	v_or_b32_e32 v6, v0, v213
	v_or_b32_e32 v0, v0, v228
	global_load_dwordx4 v[162:165], v[2:3], off
	global_load_dwordx4 v[166:169], v[2:3], off offset:64
	global_load_dwordx4 v[170:173], v[2:3], off offset:128
	global_load_dwordx4 v[174:177], v[2:3], off offset:192
	global_load_dwordx4 v[178:181], v[4:5], off
	global_load_dwordx4 v[182:185], v[4:5], off offset:64
	global_load_dwordx4 v[186:189], v[4:5], off offset:128
	global_load_dwordx4 v[190:193], v[4:5], off offset:192
	s_add_i32 m0, s38, 0x10000
	v_add_u32_e32 v0, 0xc000, v0
	global_load_lds_dwordx4 v6, s[36:37]
	s_add_i32 m0, s38, 0x10400
	s_add_i32 s3, s54, s3
	global_load_lds_dwordx4 v0, s[36:37]
	s_mul_i32 s73, s56, 0x18000
	v_add_u32_e32 v0, s73, v220
	s_cmp_lt_u32 s56, 4
	s_cbranch_scc1 .Ld16a_np
	s_setprio 1
.Ld16a_np:
	v_lshl_add_u64 v[2:3], s[8:9], 0, v[0:1]
	s_mov_b32 m0, s3
	s_mov_b64 s[36:37], 0x80
	global_load_lds_dwordx4 v0, s[8:9]
	v_lshl_add_u64 v[4:5], v[2:3], 0, s[36:37]
	s_add_i32 m0, s3, 0x400
	s_mov_b64 s[36:37], 0x100
	global_load_lds_dwordx4 v[4:5], off
	v_lshl_add_u64 v[4:5], v[2:3], 0, s[36:37]
	s_add_i32 m0, s3, 0x800
	s_mov_b64 s[36:37], 0x180
	global_load_lds_dwordx4 v[4:5], off
	v_lshl_add_u64 v[2:3], v[2:3], 0, s[36:37]
	s_add_i32 m0, s3, 0xc00
	v_add3_u32 v0, v215, v7, s58
	global_load_lds_dwordx4 v[2:3], off
	v_mul_lo_u32 v0, v0, s45
	v_or_b32_e32 v0, v216, v0
	v_readlane_b32 s36, v251, 40
	v_lshlrev_b32_e32 v0, 1, v0
	v_readlane_b32 s37, v251, 41
	s_mul_i32 s56, s56, 0x18000
	v_mov_b32_e32 v14, v1
	v_add_u32_e32 v0, s56, v220
	v_lshl_add_u64 v[196:197], s[36:37], 0, v[0:1]
	v_add3_u32 v0, v226, s56, v228
	v_lshl_add_u64 v[198:199], s[34:35], 0, v[0:1]
	v_add_u32_e32 v0, s56, v227
	v_mov_b32_e32 v15, v1
	s_waitcnt vmcnt(0)
	v_lshl_add_u64 v[200:201], s[34:35], 0, v[0:1]
	v_mov_b32_e32 v0, v1
	v_mov_b32_e32 v2, v1
	v_mov_b32_e32 v3, v1
	v_mov_b32_e32 v4, v1
	v_mov_b32_e32 v5, v1
	v_mov_b32_e32 v6, v1
	v_mov_b32_e32 v7, v1
	v_mov_b32_e32 v8, v1
	v_mov_b32_e32 v9, v1
	v_mov_b32_e32 v10, v1
	v_mov_b32_e32 v11, v1
	v_mov_b32_e32 v12, v1
	v_mov_b32_e32 v13, v1
	s_waitcnt vmcnt(0)
	v_mov_b64_e32 v[128:129], v[14:15]
	v_mov_b64_e32 v[112:113], v[14:15]
	v_mov_b64_e32 v[96:97], v[14:15]
	v_mov_b64_e32 v[80:81], v[14:15]
	v_mov_b64_e32 v[64:65], v[14:15]
	v_mov_b64_e32 v[48:49], v[14:15]
	v_mov_b64_e32 v[32:33], v[14:15]
	v_mov_b64_e32 v[126:127], v[12:13]
	v_mov_b64_e32 v[124:125], v[10:11]
	v_mov_b64_e32 v[122:123], v[8:9]
	v_mov_b64_e32 v[120:121], v[6:7]
	v_mov_b64_e32 v[118:119], v[4:5]
	v_mov_b64_e32 v[116:117], v[2:3]
	v_mov_b64_e32 v[114:115], v[0:1]
	v_mov_b64_e32 v[110:111], v[12:13]
	v_mov_b64_e32 v[108:109], v[10:11]
	v_mov_b64_e32 v[106:107], v[8:9]
	v_mov_b64_e32 v[104:105], v[6:7]
	v_mov_b64_e32 v[102:103], v[4:5]
	v_mov_b64_e32 v[100:101], v[2:3]
	v_mov_b64_e32 v[98:99], v[0:1]
	v_mov_b64_e32 v[94:95], v[12:13]
	v_mov_b64_e32 v[92:93], v[10:11]
	v_mov_b64_e32 v[90:91], v[8:9]
	v_mov_b64_e32 v[88:89], v[6:7]
	v_mov_b64_e32 v[86:87], v[4:5]
	v_mov_b64_e32 v[84:85], v[2:3]
	v_mov_b64_e32 v[82:83], v[0:1]
	v_mov_b64_e32 v[78:79], v[12:13]
	v_mov_b64_e32 v[76:77], v[10:11]
	v_mov_b64_e32 v[74:75], v[8:9]
	v_mov_b64_e32 v[72:73], v[6:7]
	v_mov_b64_e32 v[70:71], v[4:5]
	v_mov_b64_e32 v[68:69], v[2:3]
	v_mov_b64_e32 v[66:67], v[0:1]
	v_mov_b64_e32 v[62:63], v[12:13]
	v_mov_b64_e32 v[60:61], v[10:11]
	v_mov_b64_e32 v[58:59], v[8:9]
	v_mov_b64_e32 v[56:57], v[6:7]
	v_mov_b64_e32 v[54:55], v[4:5]
	v_mov_b64_e32 v[52:53], v[2:3]
	v_mov_b64_e32 v[50:51], v[0:1]
	v_mov_b64_e32 v[46:47], v[12:13]
	v_mov_b64_e32 v[44:45], v[10:11]
	v_mov_b64_e32 v[42:43], v[8:9]
	v_mov_b64_e32 v[40:41], v[6:7]
	v_mov_b64_e32 v[38:39], v[4:5]
	v_mov_b64_e32 v[36:37], v[2:3]
	v_mov_b64_e32 v[34:35], v[0:1]
	v_mov_b64_e32 v[30:31], v[12:13]
	v_mov_b64_e32 v[28:29], v[10:11]
	v_mov_b64_e32 v[26:27], v[8:9]
	v_mov_b64_e32 v[24:25], v[6:7]
	v_mov_b64_e32 v[22:23], v[4:5]
	v_mov_b64_e32 v[20:21], v[2:3]
	v_mov_b64_e32 v[18:19], v[0:1]
	v_mov_b64_e32 v[16:17], v[14:15]
	s_mov_b32 s3, s61
	v_add_u32_e32 v233, s4, v221
	v_and_b32_e32 v232, 15, v209
	v_lshl_add_u32 v232, v232, 2, s57
	v_lshl_add_u32 v231, v212, 4, s57
	v_mov_b32_e32 v237, 0xf149f2ca
	s_movk_i32 s56, 0x7f
	s_mov_b64 s[34:35], s[6:7]
	s_mov_b32 s57, 2
	v_mov_b64_e32 v[14:15], v[12:13]
	v_mov_b64_e32 v[12:13], v[10:11]
	v_mov_b64_e32 v[10:11], v[8:9]
	v_mov_b64_e32 v[8:9], v[6:7]
	v_mov_b64_e32 v[6:7], v[4:5]
	v_mov_b64_e32 v[4:5], v[2:3]
	v_mov_b64_e32 v[2:3], v[0:1]
	v_mov_b32_e32 v0, 0
	v_mov_b32_e32 v222, 0xf149f2ca
	v_mov_b32_e32 v223, 0
	v_mov_b32_e32 v225, 0xf149f2ca
	v_mov_b32_e32 v236, 0xf149f2ca
	s_waitcnt lgkmcnt(0)
	s_barrier
	s_branch .LBB0_788

.LBB0_2405:
	s_lshr_b32 s56, s51, 1
	s_lshl_b32 s2, s56, 7
	v_readlane_b32 s3, v251, 38
	s_add_i32 s4, s3, s2
	s_lshl_b64 s[38:39], s[4:5], 1
	s_bitcmp0_b32 s51, 0
	v_readlane_b32 s2, v251, 34
	v_readlane_b32 s3, v251, 36
	s_cselect_b32 s3, s3, s2
	v_readlane_b32 s64, v251, 32
	s_or_b32 s2, s64, s3
	s_mul_hi_u32 s4, s2, 0x3000
	v_readlane_b32 s36, v251, 44
	s_add_i32 s4, s4, s36
	s_mul_i32 s36, s2, 0x3000
	s_add_u32 s36, s48, s36
	s_addc_u32 s4, s49, s4
	s_add_u32 s42, s36, s38
	s_addc_u32 s43, s4, s39
	s_add_u32 s40, s44, s38
	v_readfirstlane_b32 s4, v208
	s_addc_u32 s41, s45, s39
	s_ashr_i32 s60, s4, 6
	s_and_b32 s4, s4, 0x3fffffc0
	s_lshl_b32 s4, s4, 2
	s_lshl_b32 s37, s60, 3
	s_lshl_b32 s36, s60, 5
	s_add_i32 s4, s4, 0
	v_or_b32_e32 v0, s37, v212
	v_bitop3_b32 v7, s37, v229, v214 bitop3:0xc8
	s_lshl_b32 s37, s60, 2
	s_add_i32 s61, s4, 0x18000
	s_add_i32 s4, s36, s3
	s_and_b32 s62, s37, 4
	s_lshl_b32 s57, s60, 11
	s_lshl_b32 s58, s60, 12
	s_ashr_i32 s37, s36, 31
	s_mul_i32 s59, s60, 0x60000
	s_mul_hi_i32 s63, s36, 0x3000
	s_add_u32 s42, s42, s59
	v_or3_b32 v2, v215, v7, s62
	s_addc_u32 s43, s43, s63
	s_lshr_b32 s3, s3, 6
	v_mul_lo_u32 v2, v2, s52
	s_or_b32 s59, s3, 3
	v_or_b32_e32 v8, v2, v216
	v_lshl_add_u64 v[2:3], s[42:43], 0, v[194:195]
	s_mov_b64 s[42:43], 0x30000
	s_cmp_lg_u32 0, -1
	v_lshl_add_u64 v[4:5], v[2:3], 0, s[42:43]
	s_movk_i32 s42, 0x1000
	s_cselect_b32 s3, 0, 0
	v_mul_lo_u32 v0, v0, s50
	s_add_i32 s42, s3, s57
	v_or_b32_e32 v6, v0, v213
	v_or_b32_e32 v0, v0, v228
	global_load_dwordx4 v[162:165], v[2:3], off
	global_load_dwordx4 v[166:169], v[2:3], off offset:64
	global_load_dwordx4 v[170:173], v[2:3], off offset:128
	global_load_dwordx4 v[174:177], v[2:3], off offset:192
	global_load_dwordx4 v[178:181], v[4:5], off
	global_load_dwordx4 v[182:185], v[4:5], off offset:64
	global_load_dwordx4 v[186:189], v[4:5], off offset:128
	global_load_dwordx4 v[190:193], v[4:5], off offset:192
	s_add_i32 m0, s42, 0x10000
	v_add_u32_e32 v0, 0xc000, v0
	global_load_lds_dwordx4 v6, s[40:41]
	s_add_i32 m0, s42, 0x10400
	s_add_i32 s3, s58, s3
	global_load_lds_dwordx4 v0, s[40:41]
	s_mul_i32 s73, s60, 0x18000
	v_add_u32_e32 v0, s73, v220
	s_cmp_lt_u32 s60, 4
	s_cbranch_scc1 .Ld16c_np
	s_setprio 1
.Ld16c_np:
	v_lshl_add_u64 v[2:3], s[8:9], 0, v[0:1]
	s_mov_b32 m0, s3
	s_mov_b64 s[40:41], 0x80
	global_load_lds_dwordx4 v0, s[8:9]
	v_lshl_add_u64 v[4:5], v[2:3], 0, s[40:41]
	s_add_i32 m0, s3, 0x400
	v_add3_u32 v0, v215, v7, s62
	global_load_lds_dwordx4 v[4:5], off
	v_lshl_add_u64 v[4:5], v[2:3], 0, s[10:11]
	s_add_i32 m0, s3, 0x800
	v_lshl_add_u64 v[2:3], v[2:3], 0, s[12:13]
	global_load_lds_dwordx4 v[4:5], off
	s_add_i32 m0, s3, 0xc00
	v_mul_lo_u32 v0, v0, s52
	global_load_lds_dwordx4 v[2:3], off
	v_or_b32_e32 v0, v216, v0
	v_readlane_b32 s40, v251, 40
	v_lshlrev_b32_e32 v0, 1, v0
	v_readlane_b32 s41, v251, 41
	s_mul_i32 s60, s60, 0x18000
	v_mov_b32_e32 v14, v1
	v_add_u32_e32 v0, s60, v220
	v_lshl_add_u64 v[196:197], s[40:41], 0, v[0:1]
	v_add3_u32 v0, v226, s60, v228
	v_lshl_add_u64 v[198:199], s[38:39], 0, v[0:1]
	v_add_u32_e32 v0, s60, v227
	v_mov_b32_e32 v15, v1
	s_waitcnt vmcnt(0)
	v_lshl_add_u64 v[200:201], s[38:39], 0, v[0:1]
	v_mov_b32_e32 v0, v1
	v_mov_b32_e32 v2, v1
	v_mov_b32_e32 v3, v1
	v_mov_b32_e32 v4, v1
	v_mov_b32_e32 v5, v1
	v_mov_b32_e32 v6, v1
	v_mov_b32_e32 v7, v1
	v_mov_b32_e32 v8, v1
	v_mov_b32_e32 v9, v1
	v_mov_b32_e32 v10, v1
	v_mov_b32_e32 v11, v1
	v_mov_b32_e32 v12, v1
	v_mov_b32_e32 v13, v1
	s_waitcnt vmcnt(0)
	v_mov_b64_e32 v[128:129], v[14:15]
	v_mov_b64_e32 v[112:113], v[14:15]
	v_mov_b64_e32 v[96:97], v[14:15]
	v_mov_b64_e32 v[80:81], v[14:15]
	v_mov_b64_e32 v[64:65], v[14:15]
	v_mov_b64_e32 v[48:49], v[14:15]
	v_mov_b64_e32 v[32:33], v[14:15]
	v_readlane_b32 s65, v251, 33
	v_mov_b64_e32 v[126:127], v[12:13]
	v_mov_b64_e32 v[124:125], v[10:11]
	v_mov_b64_e32 v[122:123], v[8:9]
	v_mov_b64_e32 v[120:121], v[6:7]
	v_mov_b64_e32 v[118:119], v[4:5]
	v_mov_b64_e32 v[116:117], v[2:3]
	v_mov_b64_e32 v[114:115], v[0:1]
	v_mov_b64_e32 v[110:111], v[12:13]
	v_mov_b64_e32 v[108:109], v[10:11]
	v_mov_b64_e32 v[106:107], v[8:9]
	v_mov_b64_e32 v[104:105], v[6:7]
	v_mov_b64_e32 v[102:103], v[4:5]
	v_mov_b64_e32 v[100:101], v[2:3]
	v_mov_b64_e32 v[98:99], v[0:1]
	v_mov_b64_e32 v[94:95], v[12:13]
	v_mov_b64_e32 v[92:93], v[10:11]
	v_mov_b64_e32 v[90:91], v[8:9]
	v_mov_b64_e32 v[88:89], v[6:7]
	v_mov_b64_e32 v[86:87], v[4:5]
	v_mov_b64_e32 v[84:85], v[2:3]
	v_mov_b64_e32 v[82:83], v[0:1]
	v_mov_b64_e32 v[78:79], v[12:13]
	v_mov_b64_e32 v[76:77], v[10:11]
	v_mov_b64_e32 v[74:75], v[8:9]
	v_mov_b64_e32 v[72:73], v[6:7]
	v_mov_b64_e32 v[70:71], v[4:5]
	v_mov_b64_e32 v[68:69], v[2:3]
	v_mov_b64_e32 v[66:67], v[0:1]
	v_mov_b64_e32 v[62:63], v[12:13]
	v_mov_b64_e32 v[60:61], v[10:11]
	v_mov_b64_e32 v[58:59], v[8:9]
	v_mov_b64_e32 v[56:57], v[6:7]
	v_mov_b64_e32 v[54:55], v[4:5]
	v_mov_b64_e32 v[52:53], v[2:3]
	v_mov_b64_e32 v[50:51], v[0:1]
	v_mov_b64_e32 v[46:47], v[12:13]
	v_mov_b64_e32 v[44:45], v[10:11]
	v_mov_b64_e32 v[42:43], v[8:9]
	v_mov_b64_e32 v[40:41], v[6:7]
	v_mov_b64_e32 v[38:39], v[4:5]
	v_mov_b64_e32 v[36:37], v[2:3]
	v_mov_b64_e32 v[34:35], v[0:1]
	v_mov_b64_e32 v[30:31], v[12:13]
	v_mov_b64_e32 v[28:29], v[10:11]
	v_mov_b64_e32 v[26:27], v[8:9]
	v_mov_b64_e32 v[24:25], v[6:7]
	v_mov_b64_e32 v[22:23], v[4:5]
	v_mov_b64_e32 v[20:21], v[2:3]
	v_mov_b64_e32 v[18:19], v[0:1]
	v_mov_b64_e32 v[16:17], v[14:15]
	s_mov_b32 s3, s65
	v_add_u32_e32 v233, s4, v221
	v_and_b32_e32 v232, 15, v209
	v_lshl_add_u32 v232, v232, 2, s61
	v_lshl_add_u32 v231, v212, 4, s61
	v_mov_b32_e32 v237, 0xf149f2ca
	s_movk_i32 s60, 0x7f
	s_mov_b64 s[38:39], s[6:7]
	s_mov_b32 s61, 2
	v_mov_b64_e32 v[14:15], v[12:13]
	v_mov_b64_e32 v[12:13], v[10:11]
	v_mov_b64_e32 v[10:11], v[8:9]
	v_mov_b64_e32 v[8:9], v[6:7]
	v_mov_b64_e32 v[6:7], v[4:5]
	v_mov_b64_e32 v[4:5], v[2:3]
	v_mov_b64_e32 v[2:3], v[0:1]
	v_mov_b32_e32 v0, 0
	v_mov_b32_e32 v222, 0xf149f2ca
	v_mov_b32_e32 v223, 0
	v_mov_b32_e32 v225, 0xf149f2ca
	v_mov_b32_e32 v236, 0xf149f2ca
	s_waitcnt lgkmcnt(0)
	s_barrier
	s_branch .LBB0_2408
